# phase-1 Hyena filter product on the f32 matrix cores (v_mfma_f32_32x32x2_f32, f32 operands and accumulate) instead of the v_pk_fma_f32 VALU loop; decay epilogue re-derived for the MFMA layout
# speedup vs baseline: 1.0181x; 1.0046x over previous
.LBB0_1326:
	s_waitcnt lgkmcnt(0)
	s_barrier
	s_movk_i32 s12, 0x104
	s_movk_i32 s13, 0x5ff
	s_lshl_b32 s4, s4, 2
	v_readlane_b32 s6, v252, 8
	v_readlane_b32 s7, v252, 9
	s_add_u32 s4, s6, s4
	s_addc_u32 s5, s7, 0
	s_lshl_b32 s11, s10, 7
	v_mov_b32_e32 v111, v1
	v_add_u32_e32 v112, 0x0, v42
	v_ashrrev_i32_e32 v113, 4, v112
	v_add_u32_e32 v108, s11, v113
	v_ashrrev_i32_e32 v109, 31, v108
	v_lshlrev_b64 v[108:109], 8, v[108:109]
	v_add_u32_e32 v110, 0x0, v46
	v_lshlrev_b32_e32 v110, 2, v110
	v_lshl_add_u64 v[108:109], s[4:5], 0, v[108:109]
	v_and_b32_e32 v110, 0xf0, v110
	v_lshl_add_u64 v[108:109], v[108:109], 0, v[110:111]
	v_mul_lo_u32 v84, v113, s12
	v_add3_u32 v84, 32, v84, v110
	global_load_dwordx4 v[68:71], v[108:109], off
	v_add_u32_e32 v112, 0x200, v42
	v_ashrrev_i32_e32 v113, 4, v112
	v_add_u32_e32 v108, s11, v113
	v_ashrrev_i32_e32 v109, 31, v108
	v_lshlrev_b64 v[108:109], 8, v[108:109]
	v_add_u32_e32 v110, 0x800, v46
	v_lshlrev_b32_e32 v110, 2, v110
	v_lshl_add_u64 v[108:109], s[4:5], 0, v[108:109]
	v_and_b32_e32 v110, 0xf0, v110
	v_lshl_add_u64 v[108:109], v[108:109], 0, v[110:111]
	v_mul_lo_u32 v85, v113, s12
	v_add3_u32 v85, 32, v85, v110
	global_load_dwordx4 v[72:75], v[108:109], off
	v_add_u32_e32 v112, 0x400, v42
	v_ashrrev_i32_e32 v113, 4, v112
	v_add_u32_e32 v108, s11, v113
	v_ashrrev_i32_e32 v109, 31, v108
	v_lshlrev_b64 v[108:109], 8, v[108:109]
	v_add_u32_e32 v110, 0x1000, v46
	v_lshlrev_b32_e32 v110, 2, v110
	v_lshl_add_u64 v[108:109], s[4:5], 0, v[108:109]
	v_and_b32_e32 v110, 0xf0, v110
	v_lshl_add_u64 v[108:109], v[108:109], 0, v[110:111]
	v_mul_lo_u32 v86, v113, s12
	v_add3_u32 v86, 32, v86, v110
	global_load_dwordx4 v[76:79], v[108:109], off
	v_add_u32_e32 v112, 0x600, v42
	v_ashrrev_i32_e32 v113, 4, v112
	v_add_u32_e32 v108, s11, v113
	v_ashrrev_i32_e32 v109, 31, v108
	v_lshlrev_b64 v[108:109], 8, v[108:109]
	v_add_u32_e32 v110, 0x1800, v46
	v_lshlrev_b32_e32 v110, 2, v110
	v_lshl_add_u64 v[108:109], s[4:5], 0, v[108:109]
	v_and_b32_e32 v110, 0xf0, v110
	v_lshl_add_u64 v[108:109], v[108:109], 0, v[110:111]
	v_mul_lo_u32 v87, v113, s12
	v_add3_u32 v87, 32, v87, v110
	global_load_dwordx4 v[80:83], v[108:109], off
	s_lshl_b32 s2, s8, 7
	s_and_b32 s11, s2, 0x780
	s_movk_i32 s12, 0x5ff
	v_readlane_b32 s16, v254, 23
	s_lshl_b32 s4, s11, 2
	v_readlane_b32 s30, v254, 37
	v_readlane_b32 s31, v254, 38
	s_add_u32 s4, s30, s4
	s_addc_u32 s5, s31, 0
	v_readlane_b32 s17, v254, 24
	v_readlane_b32 s18, v254, 25
	v_readlane_b32 s19, v254, 26
	v_readlane_b32 s20, v254, 27
	v_readlane_b32 s21, v254, 28
	v_readlane_b32 s22, v254, 29
	v_readlane_b32 s23, v254, 30
	v_readlane_b32 s24, v254, 31
	v_readlane_b32 s25, v254, 32
	v_readlane_b32 s26, v254, 33
	v_readlane_b32 s27, v254, 34
	v_readlane_b32 s28, v254, 35
	v_readlane_b32 s29, v254, 36
	v_add_u32_e32 v112, 0x0, v42
	v_ashrrev_i32_e32 v113, 5, v112
	v_ashrrev_i32_e32 v109, 31, v113
	v_mov_b32_e32 v108, v113
	v_lshlrev_b64 v[108:109], 13, v[108:109]
	v_add_u32_e32 v110, 0x0, v46
	v_lshlrev_b32_e32 v110, 2, v110
	v_lshl_add_u64 v[108:109], s[4:5], 0, v[108:109]
	v_and_b32_e32 v110, 0x1f0, v110
	v_lshl_add_u64 v[108:109], v[108:109], 0, v[110:111]
	v_lshlrev_b32_e32 v104, 9, v113
	v_add3_u32 v104, 32, v104, v110
	global_load_dwordx4 v[88:91], v[108:109], off
	v_add_u32_e32 v112, 0x200, v42
	v_ashrrev_i32_e32 v113, 5, v112
	v_ashrrev_i32_e32 v109, 31, v113
	v_mov_b32_e32 v108, v113
	v_lshlrev_b64 v[108:109], 13, v[108:109]
	v_add_u32_e32 v110, 0x800, v46
	v_lshlrev_b32_e32 v110, 2, v110
	v_lshl_add_u64 v[108:109], s[4:5], 0, v[108:109]
	v_and_b32_e32 v110, 0x1f0, v110
	v_lshl_add_u64 v[108:109], v[108:109], 0, v[110:111]
	v_lshlrev_b32_e32 v105, 9, v113
	v_add3_u32 v105, 32, v105, v110
	global_load_dwordx4 v[92:95], v[108:109], off
	v_add_u32_e32 v112, 0x400, v42
	v_ashrrev_i32_e32 v113, 5, v112
	v_ashrrev_i32_e32 v109, 31, v113
	v_mov_b32_e32 v108, v113
	v_lshlrev_b64 v[108:109], 13, v[108:109]
	v_add_u32_e32 v110, 0x1000, v46
	v_lshlrev_b32_e32 v110, 2, v110
	v_lshl_add_u64 v[108:109], s[4:5], 0, v[108:109]
	v_and_b32_e32 v110, 0x1f0, v110
	v_lshl_add_u64 v[108:109], v[108:109], 0, v[110:111]
	v_lshlrev_b32_e32 v106, 9, v113
	v_add3_u32 v106, 32, v106, v110
	global_load_dwordx4 v[96:99], v[108:109], off
	v_add_u32_e32 v112, 0x600, v42
	v_ashrrev_i32_e32 v113, 5, v112
	v_ashrrev_i32_e32 v109, 31, v113
	v_mov_b32_e32 v108, v113
	v_lshlrev_b64 v[108:109], 13, v[108:109]
	v_add_u32_e32 v110, 0x1800, v46
	v_lshlrev_b32_e32 v110, 2, v110
	v_lshl_add_u64 v[108:109], s[4:5], 0, v[108:109]
	v_and_b32_e32 v110, 0x1f0, v110
	v_lshl_add_u64 v[108:109], v[108:109], 0, v[110:111]
	v_lshlrev_b32_e32 v107, 9, v113
	v_add3_u32 v107, 32, v107, v110
	global_load_dwordx4 v[100:103], v[108:109], off
	v_and_b32_e32 v156, 31, v42
	v_bfe_u32 v157, v42, 5, 1
	v_lshrrev_b32_e32 v108, 8, v42
	v_bfe_u32 v109, v42, 6, 2
	v_lshl_add_u32 v158, v108, 6, v156
	v_lshlrev_b32_e32 v158, 2, v158
	v_lshl_add_u32 v158, v157, 9, v158
	v_add_u32_e32 v158, 0x8220, v158
	v_lshl_add_u32 v159, v109, 5, v156
	v_mul_u32_u24_e32 v159, 0x104, v159
	v_lshl_add_u32 v159, v157, 2, v159
	v_add_u32_e32 v159, 32, v159
	v_lshlrev_b32_e32 v112, 4, v157
	v_lshl_add_u32 v112, v108, 8, v112
	v_readlane_b32 s12, v254, 39
	v_readlane_b32 s13, v254, 40
	s_lshl_b32 s2, s11, 2
	s_add_u32 s12, s12, s2
	s_addc_u32 s13, s13, 0
	global_load_dwordx4 v[124:127], v112, s[12:13]
	global_load_dwordx4 v[128:131], v112, s[12:13] offset:32
	global_load_dwordx4 v[132:135], v112, s[12:13] offset:64
	global_load_dwordx4 v[136:139], v112, s[12:13] offset:96
	global_load_dwordx4 v[140:143], v112, s[12:13] offset:128
	global_load_dwordx4 v[144:147], v112, s[12:13] offset:160
	global_load_dwordx4 v[148:151], v112, s[12:13] offset:192
	global_load_dwordx4 v[152:155], v112, s[12:13] offset:224
	s_waitcnt vmcnt(15)
	ds_write2_b32 v84, v68, v69 offset1:1
	ds_write2_b32 v84, v70, v71 offset0:2 offset1:3
	s_waitcnt vmcnt(14)
	ds_write2_b32 v85, v72, v73 offset1:1
	ds_write2_b32 v85, v74, v75 offset0:2 offset1:3
	s_waitcnt vmcnt(13)
	ds_write2_b32 v86, v76, v77 offset1:1
	ds_write2_b32 v86, v78, v79 offset0:2 offset1:3
	s_waitcnt vmcnt(12)
	ds_write2_b32 v87, v80, v81 offset1:1
	ds_write2_b32 v87, v82, v83 offset0:2 offset1:3
	s_waitcnt vmcnt(11)
	ds_write_b128 v104, v[88:91] offset:33280
	s_waitcnt vmcnt(10)
	ds_write_b128 v105, v[92:95] offset:33280
	s_waitcnt vmcnt(9)
	ds_write_b128 v106, v[96:99] offset:33280
	s_waitcnt vmcnt(8)
	ds_write_b128 v107, v[100:103] offset:33280
.LBB0_1332:
	s_waitcnt lgkmcnt(0)
	s_barrier
	ds_read_b32 v160, v158 offset:0
	ds_read_b32 v161, v158 offset:128
	ds_read_b32 v162, v159
	ds_read_b32 v163, v158 offset:1024
	ds_read_b32 v164, v158 offset:1152
	ds_read_b32 v165, v159 offset:8
	ds_read_b32 v166, v158 offset:2048
	ds_read_b32 v167, v158 offset:2176
	ds_read_b32 v168, v159 offset:16
	ds_read_b32 v169, v158 offset:3072
	ds_read_b32 v170, v158 offset:3200
	ds_read_b32 v171, v159 offset:24
	s_waitcnt vmcnt(0)
	s_waitcnt lgkmcnt(9)
	v_mfma_f32_32x32x2_f32 v[124:139], v160, v162, v[124:139]
	v_mfma_f32_32x32x2_f32 v[140:155], v161, v162, v[140:155]
	ds_read_b32 v160, v158 offset:4096
	ds_read_b32 v161, v158 offset:4224
	ds_read_b32 v162, v159 offset:32
	s_waitcnt lgkmcnt(9)
	v_mfma_f32_32x32x2_f32 v[124:139], v163, v165, v[124:139]
	v_mfma_f32_32x32x2_f32 v[140:155], v164, v165, v[140:155]
	ds_read_b32 v163, v158 offset:5120
	ds_read_b32 v164, v158 offset:5248
	ds_read_b32 v165, v159 offset:40
	s_waitcnt lgkmcnt(9)
	v_mfma_f32_32x32x2_f32 v[124:139], v166, v168, v[124:139]
	v_mfma_f32_32x32x2_f32 v[140:155], v167, v168, v[140:155]
	ds_read_b32 v166, v158 offset:6144
	ds_read_b32 v167, v158 offset:6272
	ds_read_b32 v168, v159 offset:48
	s_waitcnt lgkmcnt(9)
	v_mfma_f32_32x32x2_f32 v[124:139], v169, v171, v[124:139]
	v_mfma_f32_32x32x2_f32 v[140:155], v170, v171, v[140:155]
	ds_read_b32 v169, v158 offset:7168
	ds_read_b32 v170, v158 offset:7296
	ds_read_b32 v171, v159 offset:56
	s_waitcnt lgkmcnt(9)
	v_mfma_f32_32x32x2_f32 v[124:139], v160, v162, v[124:139]
	v_mfma_f32_32x32x2_f32 v[140:155], v161, v162, v[140:155]
	ds_read_b32 v160, v158 offset:8192
	ds_read_b32 v161, v158 offset:8320
	ds_read_b32 v162, v159 offset:64
	s_waitcnt lgkmcnt(9)
	v_mfma_f32_32x32x2_f32 v[124:139], v163, v165, v[124:139]
	v_mfma_f32_32x32x2_f32 v[140:155], v164, v165, v[140:155]
	ds_read_b32 v163, v158 offset:9216
	ds_read_b32 v164, v158 offset:9344
	ds_read_b32 v165, v159 offset:72
	s_waitcnt lgkmcnt(9)
	v_mfma_f32_32x32x2_f32 v[124:139], v166, v168, v[124:139]
	v_mfma_f32_32x32x2_f32 v[140:155], v167, v168, v[140:155]
	ds_read_b32 v166, v158 offset:10240
	ds_read_b32 v167, v158 offset:10368
	ds_read_b32 v168, v159 offset:80
	s_waitcnt lgkmcnt(9)
	v_mfma_f32_32x32x2_f32 v[124:139], v169, v171, v[124:139]
	v_mfma_f32_32x32x2_f32 v[140:155], v170, v171, v[140:155]
	ds_read_b32 v169, v158 offset:11264
	ds_read_b32 v170, v158 offset:11392
	ds_read_b32 v171, v159 offset:88
	s_waitcnt lgkmcnt(9)
	v_mfma_f32_32x32x2_f32 v[124:139], v160, v162, v[124:139]
	v_mfma_f32_32x32x2_f32 v[140:155], v161, v162, v[140:155]
	ds_read_b32 v160, v158 offset:12288
	ds_read_b32 v161, v158 offset:12416
	ds_read_b32 v162, v159 offset:96
	s_waitcnt lgkmcnt(9)
	v_mfma_f32_32x32x2_f32 v[124:139], v163, v165, v[124:139]
	v_mfma_f32_32x32x2_f32 v[140:155], v164, v165, v[140:155]
	ds_read_b32 v163, v158 offset:13312
	ds_read_b32 v164, v158 offset:13440
	ds_read_b32 v165, v159 offset:104
	s_waitcnt lgkmcnt(9)
	v_mfma_f32_32x32x2_f32 v[124:139], v166, v168, v[124:139]
	v_mfma_f32_32x32x2_f32 v[140:155], v167, v168, v[140:155]
	ds_read_b32 v166, v158 offset:14336
	ds_read_b32 v167, v158 offset:14464
	ds_read_b32 v168, v159 offset:112
	s_waitcnt lgkmcnt(9)
	v_mfma_f32_32x32x2_f32 v[124:139], v169, v171, v[124:139]
	v_mfma_f32_32x32x2_f32 v[140:155], v170, v171, v[140:155]
	ds_read_b32 v169, v158 offset:15360
	ds_read_b32 v170, v158 offset:15488
	ds_read_b32 v171, v159 offset:120
	s_waitcnt lgkmcnt(9)
	v_mfma_f32_32x32x2_f32 v[124:139], v160, v162, v[124:139]
	v_mfma_f32_32x32x2_f32 v[140:155], v161, v162, v[140:155]
	ds_read_b32 v160, v158 offset:16384
	ds_read_b32 v161, v158 offset:16512
	ds_read_b32 v162, v159 offset:128
	s_waitcnt lgkmcnt(9)
	v_mfma_f32_32x32x2_f32 v[124:139], v163, v165, v[124:139]
	v_mfma_f32_32x32x2_f32 v[140:155], v164, v165, v[140:155]
	ds_read_b32 v163, v158 offset:17408
	ds_read_b32 v164, v158 offset:17536
	ds_read_b32 v165, v159 offset:136
	s_waitcnt lgkmcnt(9)
	v_mfma_f32_32x32x2_f32 v[124:139], v166, v168, v[124:139]
	v_mfma_f32_32x32x2_f32 v[140:155], v167, v168, v[140:155]
	ds_read_b32 v166, v158 offset:18432
	ds_read_b32 v167, v158 offset:18560
	ds_read_b32 v168, v159 offset:144
	s_waitcnt lgkmcnt(9)
	v_mfma_f32_32x32x2_f32 v[124:139], v169, v171, v[124:139]
	v_mfma_f32_32x32x2_f32 v[140:155], v170, v171, v[140:155]
	ds_read_b32 v169, v158 offset:19456
	ds_read_b32 v170, v158 offset:19584
	ds_read_b32 v171, v159 offset:152
	s_waitcnt lgkmcnt(9)
	v_mfma_f32_32x32x2_f32 v[124:139], v160, v162, v[124:139]
	v_mfma_f32_32x32x2_f32 v[140:155], v161, v162, v[140:155]
	ds_read_b32 v160, v158 offset:20480
	ds_read_b32 v161, v158 offset:20608
	ds_read_b32 v162, v159 offset:160
	s_waitcnt lgkmcnt(9)
	v_mfma_f32_32x32x2_f32 v[124:139], v163, v165, v[124:139]
	v_mfma_f32_32x32x2_f32 v[140:155], v164, v165, v[140:155]
	ds_read_b32 v163, v158 offset:21504
	ds_read_b32 v164, v158 offset:21632
	ds_read_b32 v165, v159 offset:168
	s_waitcnt lgkmcnt(9)
	v_mfma_f32_32x32x2_f32 v[124:139], v166, v168, v[124:139]
	v_mfma_f32_32x32x2_f32 v[140:155], v167, v168, v[140:155]
	ds_read_b32 v166, v158 offset:22528
	ds_read_b32 v167, v158 offset:22656
	ds_read_b32 v168, v159 offset:176
	s_waitcnt lgkmcnt(9)
	v_mfma_f32_32x32x2_f32 v[124:139], v169, v171, v[124:139]
	v_mfma_f32_32x32x2_f32 v[140:155], v170, v171, v[140:155]
	ds_read_b32 v169, v158 offset:23552
	ds_read_b32 v170, v158 offset:23680
	ds_read_b32 v171, v159 offset:184
	s_waitcnt lgkmcnt(9)
	v_mfma_f32_32x32x2_f32 v[124:139], v160, v162, v[124:139]
	v_mfma_f32_32x32x2_f32 v[140:155], v161, v162, v[140:155]
	ds_read_b32 v160, v158 offset:24576
	ds_read_b32 v161, v158 offset:24704
	ds_read_b32 v162, v159 offset:192
	s_waitcnt lgkmcnt(9)
	v_mfma_f32_32x32x2_f32 v[124:139], v163, v165, v[124:139]
	v_mfma_f32_32x32x2_f32 v[140:155], v164, v165, v[140:155]
	ds_read_b32 v163, v158 offset:25600
	ds_read_b32 v164, v158 offset:25728
	ds_read_b32 v165, v159 offset:200
	s_waitcnt lgkmcnt(9)
	v_mfma_f32_32x32x2_f32 v[124:139], v166, v168, v[124:139]
	v_mfma_f32_32x32x2_f32 v[140:155], v167, v168, v[140:155]
	ds_read_b32 v166, v158 offset:26624
	ds_read_b32 v167, v158 offset:26752
	ds_read_b32 v168, v159 offset:208
	s_waitcnt lgkmcnt(9)
	v_mfma_f32_32x32x2_f32 v[124:139], v169, v171, v[124:139]
	v_mfma_f32_32x32x2_f32 v[140:155], v170, v171, v[140:155]
	ds_read_b32 v169, v158 offset:27648
	ds_read_b32 v170, v158 offset:27776
	ds_read_b32 v171, v159 offset:216
	s_waitcnt lgkmcnt(9)
	v_mfma_f32_32x32x2_f32 v[124:139], v160, v162, v[124:139]
	v_mfma_f32_32x32x2_f32 v[140:155], v161, v162, v[140:155]
	ds_read_b32 v160, v158 offset:28672
	ds_read_b32 v161, v158 offset:28800
	ds_read_b32 v162, v159 offset:224
	s_waitcnt lgkmcnt(9)
	v_mfma_f32_32x32x2_f32 v[124:139], v163, v165, v[124:139]
	v_mfma_f32_32x32x2_f32 v[140:155], v164, v165, v[140:155]
	ds_read_b32 v163, v158 offset:29696
	ds_read_b32 v164, v158 offset:29824
	ds_read_b32 v165, v159 offset:232
	s_waitcnt lgkmcnt(9)
	v_mfma_f32_32x32x2_f32 v[124:139], v166, v168, v[124:139]
	v_mfma_f32_32x32x2_f32 v[140:155], v167, v168, v[140:155]
	ds_read_b32 v166, v158 offset:30720
	ds_read_b32 v167, v158 offset:30848
	ds_read_b32 v168, v159 offset:240
	s_waitcnt lgkmcnt(9)
	v_mfma_f32_32x32x2_f32 v[124:139], v169, v171, v[124:139]
	v_mfma_f32_32x32x2_f32 v[140:155], v170, v171, v[140:155]
	ds_read_b32 v169, v158 offset:31744
	ds_read_b32 v170, v158 offset:31872
	ds_read_b32 v171, v159 offset:248
	s_waitcnt lgkmcnt(9)
	v_mfma_f32_32x32x2_f32 v[124:139], v160, v162, v[124:139]
	v_mfma_f32_32x32x2_f32 v[140:155], v161, v162, v[140:155]
	s_waitcnt lgkmcnt(6)
	v_mfma_f32_32x32x2_f32 v[124:139], v163, v165, v[124:139]
	v_mfma_f32_32x32x2_f32 v[140:155], v164, v165, v[140:155]
	s_waitcnt lgkmcnt(3)
	v_mfma_f32_32x32x2_f32 v[124:139], v166, v168, v[124:139]
	v_mfma_f32_32x32x2_f32 v[140:155], v167, v168, v[140:155]
	s_waitcnt lgkmcnt(0)
	v_mfma_f32_32x32x2_f32 v[124:139], v169, v171, v[124:139]
	v_mfma_f32_32x32x2_f32 v[140:155], v170, v171, v[140:155]
	v_lshl_add_u32 v172, s10, 7, v156
	v_lshl_add_u32 v172, v109, 5, v172
	s_add_i32 s2, s9, -1
	v_cvt_f32_u32_e32 v54, s2
	v_cvt_f32_i32_e32 v11, v172
	v_mov_b32_e32 v60, 0xc0447cbd
	v_lshl_add_u32 v174, v108, 6, s11
	v_lshl_add_u32 v174, v157, 2, v174
	v_mad_i64_i32 v[176:177], s[2:3], s9, v174, 0
	v_lshl_add_u64 v[176:177], v[176:177], 2, s[0:1]
	v_mov_b32_e32 v180, v172
	v_mov_b32_e32 v181, v1
	v_lshl_add_u64 v[176:177], v[180:181], 2, v[176:177]
	v_div_scale_f32 v24, s[2:3], v54, v54, -v11
	v_rcp_f32_e32 v25, v24
	s_mov_b32 s4, 0x3fb8aa3b
	s_mov_b32 s5, 0xc2ce8ed0
	s_mov_b32 s6, 0x42b17218
	v_fma_f32 v39, -v24, v25, 1.0
	v_fmac_f32_e32 v25, v39, v25
	v_div_scale_f32 v39, vcc, -v11, v54, -v11
	v_mul_f32_e32 v56, v39, v25
	v_fma_f32 v57, -v24, v56, v39
	v_fmac_f32_e32 v56, v57, v25
	v_fma_f32 v24, -v24, v56, v39
	v_div_fmas_f32 v24, v24, v25, v56
	v_div_fixup_f32 v173, v24, v54, -v11
	s_lshl_b32 s14, s9, 2
	s_mov_b32 s15, 0
	s_mul_i32 s16, s14, 5
	s_mov_b32 s17, 0
	s_nop 7
	s_nop 7
	s_nop 3
	v_and_b32_e32 v24, 0x1ff, v174
	v_cvt_f32_u32_e32 v24, v24
	v_fmamk_f32 v55, v24, 0xbcc4df2d, v60
	v_mul_f32_e64 v24, |v55|, v173
	v_mul_f32_e32 v25, 0x3fb8aa3b, v24
	v_fma_f32 v39, v24, s4, -v25
	v_rndne_f32_e32 v56, v25
	v_fmac_f32_e32 v39, 0x32a5705f, v24
	v_sub_f32_e32 v25, v25, v56
	v_add_f32_e32 v25, v25, v39
	v_exp_f32_e32 v25, v25
	v_cvt_i32_f32_e32 v39, v56
	v_cmp_ngt_f32_e32 vcc, s5, v24
	v_ldexp_f32 v25, v25, v39
	s_nop 0
	v_cndmask_b32_e32 v25, 0, v25, vcc
	v_cmp_nlt_f32_e32 vcc, s6, v24
	s_nop 1
	v_cndmask_b32_e32 v24, v219, v25, vcc
	v_mul_f32_e32 v124, v24, v124
	global_store_dword v[176:177], v124, off
	v_add_u32_e32 v174, 1, v174
	v_lshl_add_u64 v[176:177], v[176:177], 0, s[14:15]
	v_and_b32_e32 v24, 0x1ff, v174
	v_cvt_f32_u32_e32 v24, v24
	v_fmamk_f32 v55, v24, 0xbcc4df2d, v60
	v_mul_f32_e64 v24, |v55|, v173
	v_mul_f32_e32 v25, 0x3fb8aa3b, v24
	v_fma_f32 v39, v24, s4, -v25
	v_rndne_f32_e32 v56, v25
	v_fmac_f32_e32 v39, 0x32a5705f, v24
	v_sub_f32_e32 v25, v25, v56
	v_add_f32_e32 v25, v25, v39
	v_exp_f32_e32 v25, v25
	v_cvt_i32_f32_e32 v39, v56
	v_cmp_ngt_f32_e32 vcc, s5, v24
	v_ldexp_f32 v25, v25, v39
	s_nop 0
	v_cndmask_b32_e32 v25, 0, v25, vcc
	v_cmp_nlt_f32_e32 vcc, s6, v24
	s_nop 1
	v_cndmask_b32_e32 v24, v219, v25, vcc
	v_mul_f32_e32 v125, v24, v125
	global_store_dword v[176:177], v125, off
	v_add_u32_e32 v174, 1, v174
	v_lshl_add_u64 v[176:177], v[176:177], 0, s[14:15]
	v_and_b32_e32 v24, 0x1ff, v174
	v_cvt_f32_u32_e32 v24, v24
	v_fmamk_f32 v55, v24, 0xbcc4df2d, v60
	v_mul_f32_e64 v24, |v55|, v173
	v_mul_f32_e32 v25, 0x3fb8aa3b, v24
	v_fma_f32 v39, v24, s4, -v25
	v_rndne_f32_e32 v56, v25
	v_fmac_f32_e32 v39, 0x32a5705f, v24
	v_sub_f32_e32 v25, v25, v56
	v_add_f32_e32 v25, v25, v39
	v_exp_f32_e32 v25, v25
	v_cvt_i32_f32_e32 v39, v56
	v_cmp_ngt_f32_e32 vcc, s5, v24
	v_ldexp_f32 v25, v25, v39
	s_nop 0
	v_cndmask_b32_e32 v25, 0, v25, vcc
	v_cmp_nlt_f32_e32 vcc, s6, v24
	s_nop 1
	v_cndmask_b32_e32 v24, v219, v25, vcc
	v_mul_f32_e32 v126, v24, v126
	global_store_dword v[176:177], v126, off
	v_add_u32_e32 v174, 1, v174
	v_lshl_add_u64 v[176:177], v[176:177], 0, s[14:15]
	v_and_b32_e32 v24, 0x1ff, v174
	v_cvt_f32_u32_e32 v24, v24
	v_fmamk_f32 v55, v24, 0xbcc4df2d, v60
	v_mul_f32_e64 v24, |v55|, v173
	v_mul_f32_e32 v25, 0x3fb8aa3b, v24
	v_fma_f32 v39, v24, s4, -v25
	v_rndne_f32_e32 v56, v25
	v_fmac_f32_e32 v39, 0x32a5705f, v24
	v_sub_f32_e32 v25, v25, v56
	v_add_f32_e32 v25, v25, v39
	v_exp_f32_e32 v25, v25
	v_cvt_i32_f32_e32 v39, v56
	v_cmp_ngt_f32_e32 vcc, s5, v24
	v_ldexp_f32 v25, v25, v39
	s_nop 0
	v_cndmask_b32_e32 v25, 0, v25, vcc
	v_cmp_nlt_f32_e32 vcc, s6, v24
	s_nop 1
	v_cndmask_b32_e32 v24, v219, v25, vcc
	v_mul_f32_e32 v127, v24, v127
	global_store_dword v[176:177], v127, off
	v_add_u32_e32 v174, 5, v174
	v_lshl_add_u64 v[176:177], v[176:177], 0, s[16:17]
	v_and_b32_e32 v24, 0x1ff, v174
	v_cvt_f32_u32_e32 v24, v24
	v_fmamk_f32 v55, v24, 0xbcc4df2d, v60
	v_mul_f32_e64 v24, |v55|, v173
	v_mul_f32_e32 v25, 0x3fb8aa3b, v24
	v_fma_f32 v39, v24, s4, -v25
	v_rndne_f32_e32 v56, v25
	v_fmac_f32_e32 v39, 0x32a5705f, v24
	v_sub_f32_e32 v25, v25, v56
	v_add_f32_e32 v25, v25, v39
	v_exp_f32_e32 v25, v25
	v_cvt_i32_f32_e32 v39, v56
	v_cmp_ngt_f32_e32 vcc, s5, v24
	v_ldexp_f32 v25, v25, v39
	s_nop 0
	v_cndmask_b32_e32 v25, 0, v25, vcc
	v_cmp_nlt_f32_e32 vcc, s6, v24
	s_nop 1
	v_cndmask_b32_e32 v24, v219, v25, vcc
	v_mul_f32_e32 v128, v24, v128
	global_store_dword v[176:177], v128, off
	v_add_u32_e32 v174, 1, v174
	v_lshl_add_u64 v[176:177], v[176:177], 0, s[14:15]
	v_and_b32_e32 v24, 0x1ff, v174
	v_cvt_f32_u32_e32 v24, v24
	v_fmamk_f32 v55, v24, 0xbcc4df2d, v60
	v_mul_f32_e64 v24, |v55|, v173
	v_mul_f32_e32 v25, 0x3fb8aa3b, v24
	v_fma_f32 v39, v24, s4, -v25
	v_rndne_f32_e32 v56, v25
	v_fmac_f32_e32 v39, 0x32a5705f, v24
	v_sub_f32_e32 v25, v25, v56
	v_add_f32_e32 v25, v25, v39
	v_exp_f32_e32 v25, v25
	v_cvt_i32_f32_e32 v39, v56
	v_cmp_ngt_f32_e32 vcc, s5, v24
	v_ldexp_f32 v25, v25, v39
	s_nop 0
	v_cndmask_b32_e32 v25, 0, v25, vcc
	v_cmp_nlt_f32_e32 vcc, s6, v24
	s_nop 1
	v_cndmask_b32_e32 v24, v219, v25, vcc
	v_mul_f32_e32 v129, v24, v129
	global_store_dword v[176:177], v129, off
	v_add_u32_e32 v174, 1, v174
	v_lshl_add_u64 v[176:177], v[176:177], 0, s[14:15]
	v_and_b32_e32 v24, 0x1ff, v174
	v_cvt_f32_u32_e32 v24, v24
	v_fmamk_f32 v55, v24, 0xbcc4df2d, v60
	v_mul_f32_e64 v24, |v55|, v173
	v_mul_f32_e32 v25, 0x3fb8aa3b, v24
	v_fma_f32 v39, v24, s4, -v25
	v_rndne_f32_e32 v56, v25
	v_fmac_f32_e32 v39, 0x32a5705f, v24
	v_sub_f32_e32 v25, v25, v56
	v_add_f32_e32 v25, v25, v39
	v_exp_f32_e32 v25, v25
	v_cvt_i32_f32_e32 v39, v56
	v_cmp_ngt_f32_e32 vcc, s5, v24
	v_ldexp_f32 v25, v25, v39
	s_nop 0
	v_cndmask_b32_e32 v25, 0, v25, vcc
	v_cmp_nlt_f32_e32 vcc, s6, v24
	s_nop 1
	v_cndmask_b32_e32 v24, v219, v25, vcc
	v_mul_f32_e32 v130, v24, v130
	global_store_dword v[176:177], v130, off
	v_add_u32_e32 v174, 1, v174
	v_lshl_add_u64 v[176:177], v[176:177], 0, s[14:15]
	v_and_b32_e32 v24, 0x1ff, v174
	v_cvt_f32_u32_e32 v24, v24
	v_fmamk_f32 v55, v24, 0xbcc4df2d, v60
	v_mul_f32_e64 v24, |v55|, v173
	v_mul_f32_e32 v25, 0x3fb8aa3b, v24
	v_fma_f32 v39, v24, s4, -v25
	v_rndne_f32_e32 v56, v25
	v_fmac_f32_e32 v39, 0x32a5705f, v24
	v_sub_f32_e32 v25, v25, v56
	v_add_f32_e32 v25, v25, v39
	v_exp_f32_e32 v25, v25
	v_cvt_i32_f32_e32 v39, v56
	v_cmp_ngt_f32_e32 vcc, s5, v24
	v_ldexp_f32 v25, v25, v39
	s_nop 0
	v_cndmask_b32_e32 v25, 0, v25, vcc
	v_cmp_nlt_f32_e32 vcc, s6, v24
	s_nop 1
	v_cndmask_b32_e32 v24, v219, v25, vcc
	v_mul_f32_e32 v131, v24, v131
	global_store_dword v[176:177], v131, off
	v_add_u32_e32 v174, 5, v174
	v_lshl_add_u64 v[176:177], v[176:177], 0, s[16:17]
	v_and_b32_e32 v24, 0x1ff, v174
	v_cvt_f32_u32_e32 v24, v24
	v_fmamk_f32 v55, v24, 0xbcc4df2d, v60
	v_mul_f32_e64 v24, |v55|, v173
	v_mul_f32_e32 v25, 0x3fb8aa3b, v24
	v_fma_f32 v39, v24, s4, -v25
	v_rndne_f32_e32 v56, v25
	v_fmac_f32_e32 v39, 0x32a5705f, v24
	v_sub_f32_e32 v25, v25, v56
	v_add_f32_e32 v25, v25, v39
	v_exp_f32_e32 v25, v25
	v_cvt_i32_f32_e32 v39, v56
	v_cmp_ngt_f32_e32 vcc, s5, v24
	v_ldexp_f32 v25, v25, v39
	s_nop 0
	v_cndmask_b32_e32 v25, 0, v25, vcc
	v_cmp_nlt_f32_e32 vcc, s6, v24
	s_nop 1
	v_cndmask_b32_e32 v24, v219, v25, vcc
	v_mul_f32_e32 v132, v24, v132
	global_store_dword v[176:177], v132, off
	v_add_u32_e32 v174, 1, v174
	v_lshl_add_u64 v[176:177], v[176:177], 0, s[14:15]
	v_and_b32_e32 v24, 0x1ff, v174
	v_cvt_f32_u32_e32 v24, v24
	v_fmamk_f32 v55, v24, 0xbcc4df2d, v60
	v_mul_f32_e64 v24, |v55|, v173
	v_mul_f32_e32 v25, 0x3fb8aa3b, v24
	v_fma_f32 v39, v24, s4, -v25
	v_rndne_f32_e32 v56, v25
	v_fmac_f32_e32 v39, 0x32a5705f, v24
	v_sub_f32_e32 v25, v25, v56
	v_add_f32_e32 v25, v25, v39
	v_exp_f32_e32 v25, v25
	v_cvt_i32_f32_e32 v39, v56
	v_cmp_ngt_f32_e32 vcc, s5, v24
	v_ldexp_f32 v25, v25, v39
	s_nop 0
	v_cndmask_b32_e32 v25, 0, v25, vcc
	v_cmp_nlt_f32_e32 vcc, s6, v24
	s_nop 1
	v_cndmask_b32_e32 v24, v219, v25, vcc
	v_mul_f32_e32 v133, v24, v133
	global_store_dword v[176:177], v133, off
	v_add_u32_e32 v174, 1, v174
	v_lshl_add_u64 v[176:177], v[176:177], 0, s[14:15]
	v_and_b32_e32 v24, 0x1ff, v174
	v_cvt_f32_u32_e32 v24, v24
	v_fmamk_f32 v55, v24, 0xbcc4df2d, v60
	v_mul_f32_e64 v24, |v55|, v173
	v_mul_f32_e32 v25, 0x3fb8aa3b, v24
	v_fma_f32 v39, v24, s4, -v25
	v_rndne_f32_e32 v56, v25
	v_fmac_f32_e32 v39, 0x32a5705f, v24
	v_sub_f32_e32 v25, v25, v56
	v_add_f32_e32 v25, v25, v39
	v_exp_f32_e32 v25, v25
	v_cvt_i32_f32_e32 v39, v56
	v_cmp_ngt_f32_e32 vcc, s5, v24
	v_ldexp_f32 v25, v25, v39
	s_nop 0
	v_cndmask_b32_e32 v25, 0, v25, vcc
	v_cmp_nlt_f32_e32 vcc, s6, v24
	s_nop 1
	v_cndmask_b32_e32 v24, v219, v25, vcc
	v_mul_f32_e32 v134, v24, v134
	global_store_dword v[176:177], v134, off
	v_add_u32_e32 v174, 1, v174
	v_lshl_add_u64 v[176:177], v[176:177], 0, s[14:15]
	v_and_b32_e32 v24, 0x1ff, v174
	v_cvt_f32_u32_e32 v24, v24
	v_fmamk_f32 v55, v24, 0xbcc4df2d, v60
	v_mul_f32_e64 v24, |v55|, v173
	v_mul_f32_e32 v25, 0x3fb8aa3b, v24
	v_fma_f32 v39, v24, s4, -v25
	v_rndne_f32_e32 v56, v25
	v_fmac_f32_e32 v39, 0x32a5705f, v24
	v_sub_f32_e32 v25, v25, v56
	v_add_f32_e32 v25, v25, v39
	v_exp_f32_e32 v25, v25
	v_cvt_i32_f32_e32 v39, v56
	v_cmp_ngt_f32_e32 vcc, s5, v24
	v_ldexp_f32 v25, v25, v39
	s_nop 0
	v_cndmask_b32_e32 v25, 0, v25, vcc
	v_cmp_nlt_f32_e32 vcc, s6, v24
	s_nop 1
	v_cndmask_b32_e32 v24, v219, v25, vcc
	v_mul_f32_e32 v135, v24, v135
	global_store_dword v[176:177], v135, off
	v_add_u32_e32 v174, 5, v174
	v_lshl_add_u64 v[176:177], v[176:177], 0, s[16:17]
	v_and_b32_e32 v24, 0x1ff, v174
	v_cvt_f32_u32_e32 v24, v24
	v_fmamk_f32 v55, v24, 0xbcc4df2d, v60
	v_mul_f32_e64 v24, |v55|, v173
	v_mul_f32_e32 v25, 0x3fb8aa3b, v24
	v_fma_f32 v39, v24, s4, -v25
	v_rndne_f32_e32 v56, v25
	v_fmac_f32_e32 v39, 0x32a5705f, v24
	v_sub_f32_e32 v25, v25, v56
	v_add_f32_e32 v25, v25, v39
	v_exp_f32_e32 v25, v25
	v_cvt_i32_f32_e32 v39, v56
	v_cmp_ngt_f32_e32 vcc, s5, v24
	v_ldexp_f32 v25, v25, v39
	s_nop 0
	v_cndmask_b32_e32 v25, 0, v25, vcc
	v_cmp_nlt_f32_e32 vcc, s6, v24
	s_nop 1
	v_cndmask_b32_e32 v24, v219, v25, vcc
	v_mul_f32_e32 v136, v24, v136
	global_store_dword v[176:177], v136, off
	v_add_u32_e32 v174, 1, v174
	v_lshl_add_u64 v[176:177], v[176:177], 0, s[14:15]
	v_and_b32_e32 v24, 0x1ff, v174
	v_cvt_f32_u32_e32 v24, v24
	v_fmamk_f32 v55, v24, 0xbcc4df2d, v60
	v_mul_f32_e64 v24, |v55|, v173
	v_mul_f32_e32 v25, 0x3fb8aa3b, v24
	v_fma_f32 v39, v24, s4, -v25
	v_rndne_f32_e32 v56, v25
	v_fmac_f32_e32 v39, 0x32a5705f, v24
	v_sub_f32_e32 v25, v25, v56
	v_add_f32_e32 v25, v25, v39
	v_exp_f32_e32 v25, v25
	v_cvt_i32_f32_e32 v39, v56
	v_cmp_ngt_f32_e32 vcc, s5, v24
	v_ldexp_f32 v25, v25, v39
	s_nop 0
	v_cndmask_b32_e32 v25, 0, v25, vcc
	v_cmp_nlt_f32_e32 vcc, s6, v24
	s_nop 1
	v_cndmask_b32_e32 v24, v219, v25, vcc
	v_mul_f32_e32 v137, v24, v137
	global_store_dword v[176:177], v137, off
	v_add_u32_e32 v174, 1, v174
	v_lshl_add_u64 v[176:177], v[176:177], 0, s[14:15]
	v_and_b32_e32 v24, 0x1ff, v174
	v_cvt_f32_u32_e32 v24, v24
	v_fmamk_f32 v55, v24, 0xbcc4df2d, v60
	v_mul_f32_e64 v24, |v55|, v173
	v_mul_f32_e32 v25, 0x3fb8aa3b, v24
	v_fma_f32 v39, v24, s4, -v25
	v_rndne_f32_e32 v56, v25
	v_fmac_f32_e32 v39, 0x32a5705f, v24
	v_sub_f32_e32 v25, v25, v56
	v_add_f32_e32 v25, v25, v39
	v_exp_f32_e32 v25, v25
	v_cvt_i32_f32_e32 v39, v56
	v_cmp_ngt_f32_e32 vcc, s5, v24
	v_ldexp_f32 v25, v25, v39
	s_nop 0
	v_cndmask_b32_e32 v25, 0, v25, vcc
	v_cmp_nlt_f32_e32 vcc, s6, v24
	s_nop 1
	v_cndmask_b32_e32 v24, v219, v25, vcc
	v_mul_f32_e32 v138, v24, v138
	global_store_dword v[176:177], v138, off
	v_add_u32_e32 v174, 1, v174
	v_lshl_add_u64 v[176:177], v[176:177], 0, s[14:15]
	v_and_b32_e32 v24, 0x1ff, v174
	v_cvt_f32_u32_e32 v24, v24
	v_fmamk_f32 v55, v24, 0xbcc4df2d, v60
	v_mul_f32_e64 v24, |v55|, v173
	v_mul_f32_e32 v25, 0x3fb8aa3b, v24
	v_fma_f32 v39, v24, s4, -v25
	v_rndne_f32_e32 v56, v25
	v_fmac_f32_e32 v39, 0x32a5705f, v24
	v_sub_f32_e32 v25, v25, v56
	v_add_f32_e32 v25, v25, v39
	v_exp_f32_e32 v25, v25
	v_cvt_i32_f32_e32 v39, v56
	v_cmp_ngt_f32_e32 vcc, s5, v24
	v_ldexp_f32 v25, v25, v39
	s_nop 0
	v_cndmask_b32_e32 v25, 0, v25, vcc
	v_cmp_nlt_f32_e32 vcc, s6, v24
	s_nop 1
	v_cndmask_b32_e32 v24, v219, v25, vcc
	v_mul_f32_e32 v139, v24, v139
	global_store_dword v[176:177], v139, off
	v_add_u32_e32 v174, 5, v174
	v_lshl_add_u64 v[176:177], v[176:177], 0, s[16:17]
	v_and_b32_e32 v24, 0x1ff, v174
	v_cvt_f32_u32_e32 v24, v24
	v_fmamk_f32 v55, v24, 0xbcc4df2d, v60
	v_mul_f32_e64 v24, |v55|, v173
	v_mul_f32_e32 v25, 0x3fb8aa3b, v24
	v_fma_f32 v39, v24, s4, -v25
	v_rndne_f32_e32 v56, v25
	v_fmac_f32_e32 v39, 0x32a5705f, v24
	v_sub_f32_e32 v25, v25, v56
	v_add_f32_e32 v25, v25, v39
	v_exp_f32_e32 v25, v25
	v_cvt_i32_f32_e32 v39, v56
	v_cmp_ngt_f32_e32 vcc, s5, v24
	v_ldexp_f32 v25, v25, v39
	s_nop 0
	v_cndmask_b32_e32 v25, 0, v25, vcc
	v_cmp_nlt_f32_e32 vcc, s6, v24
	s_nop 1
	v_cndmask_b32_e32 v24, v219, v25, vcc
	v_mul_f32_e32 v140, v24, v140
	global_store_dword v[176:177], v140, off
	v_add_u32_e32 v174, 1, v174
	v_lshl_add_u64 v[176:177], v[176:177], 0, s[14:15]
	v_and_b32_e32 v24, 0x1ff, v174
	v_cvt_f32_u32_e32 v24, v24
	v_fmamk_f32 v55, v24, 0xbcc4df2d, v60
	v_mul_f32_e64 v24, |v55|, v173
	v_mul_f32_e32 v25, 0x3fb8aa3b, v24
	v_fma_f32 v39, v24, s4, -v25
	v_rndne_f32_e32 v56, v25
	v_fmac_f32_e32 v39, 0x32a5705f, v24
	v_sub_f32_e32 v25, v25, v56
	v_add_f32_e32 v25, v25, v39
	v_exp_f32_e32 v25, v25
	v_cvt_i32_f32_e32 v39, v56
	v_cmp_ngt_f32_e32 vcc, s5, v24
	v_ldexp_f32 v25, v25, v39
	s_nop 0
	v_cndmask_b32_e32 v25, 0, v25, vcc
	v_cmp_nlt_f32_e32 vcc, s6, v24
	s_nop 1
	v_cndmask_b32_e32 v24, v219, v25, vcc
	v_mul_f32_e32 v141, v24, v141
	global_store_dword v[176:177], v141, off
	v_add_u32_e32 v174, 1, v174
	v_lshl_add_u64 v[176:177], v[176:177], 0, s[14:15]
	v_and_b32_e32 v24, 0x1ff, v174
	v_cvt_f32_u32_e32 v24, v24
	v_fmamk_f32 v55, v24, 0xbcc4df2d, v60
	v_mul_f32_e64 v24, |v55|, v173
	v_mul_f32_e32 v25, 0x3fb8aa3b, v24
	v_fma_f32 v39, v24, s4, -v25
	v_rndne_f32_e32 v56, v25
	v_fmac_f32_e32 v39, 0x32a5705f, v24
	v_sub_f32_e32 v25, v25, v56
	v_add_f32_e32 v25, v25, v39
	v_exp_f32_e32 v25, v25
	v_cvt_i32_f32_e32 v39, v56
	v_cmp_ngt_f32_e32 vcc, s5, v24
	v_ldexp_f32 v25, v25, v39
	s_nop 0
	v_cndmask_b32_e32 v25, 0, v25, vcc
	v_cmp_nlt_f32_e32 vcc, s6, v24
	s_nop 1
	v_cndmask_b32_e32 v24, v219, v25, vcc
	v_mul_f32_e32 v142, v24, v142
	global_store_dword v[176:177], v142, off
	v_add_u32_e32 v174, 1, v174
	v_lshl_add_u64 v[176:177], v[176:177], 0, s[14:15]
	v_and_b32_e32 v24, 0x1ff, v174
	v_cvt_f32_u32_e32 v24, v24
	v_fmamk_f32 v55, v24, 0xbcc4df2d, v60
	v_mul_f32_e64 v24, |v55|, v173
	v_mul_f32_e32 v25, 0x3fb8aa3b, v24
	v_fma_f32 v39, v24, s4, -v25
	v_rndne_f32_e32 v56, v25
	v_fmac_f32_e32 v39, 0x32a5705f, v24
	v_sub_f32_e32 v25, v25, v56
	v_add_f32_e32 v25, v25, v39
	v_exp_f32_e32 v25, v25
	v_cvt_i32_f32_e32 v39, v56
	v_cmp_ngt_f32_e32 vcc, s5, v24
	v_ldexp_f32 v25, v25, v39
	s_nop 0
	v_cndmask_b32_e32 v25, 0, v25, vcc
	v_cmp_nlt_f32_e32 vcc, s6, v24
	s_nop 1
	v_cndmask_b32_e32 v24, v219, v25, vcc
	v_mul_f32_e32 v143, v24, v143
	global_store_dword v[176:177], v143, off
	v_add_u32_e32 v174, 5, v174
	v_lshl_add_u64 v[176:177], v[176:177], 0, s[16:17]
	v_and_b32_e32 v24, 0x1ff, v174
	v_cvt_f32_u32_e32 v24, v24
	v_fmamk_f32 v55, v24, 0xbcc4df2d, v60
	v_mul_f32_e64 v24, |v55|, v173
	v_mul_f32_e32 v25, 0x3fb8aa3b, v24
	v_fma_f32 v39, v24, s4, -v25
	v_rndne_f32_e32 v56, v25
	v_fmac_f32_e32 v39, 0x32a5705f, v24
	v_sub_f32_e32 v25, v25, v56
	v_add_f32_e32 v25, v25, v39
	v_exp_f32_e32 v25, v25
	v_cvt_i32_f32_e32 v39, v56
	v_cmp_ngt_f32_e32 vcc, s5, v24
	v_ldexp_f32 v25, v25, v39
	s_nop 0
	v_cndmask_b32_e32 v25, 0, v25, vcc
	v_cmp_nlt_f32_e32 vcc, s6, v24
	s_nop 1
	v_cndmask_b32_e32 v24, v219, v25, vcc
	v_mul_f32_e32 v144, v24, v144
	global_store_dword v[176:177], v144, off
	v_add_u32_e32 v174, 1, v174
	v_lshl_add_u64 v[176:177], v[176:177], 0, s[14:15]
	v_and_b32_e32 v24, 0x1ff, v174
	v_cvt_f32_u32_e32 v24, v24
	v_fmamk_f32 v55, v24, 0xbcc4df2d, v60
	v_mul_f32_e64 v24, |v55|, v173
	v_mul_f32_e32 v25, 0x3fb8aa3b, v24
	v_fma_f32 v39, v24, s4, -v25
	v_rndne_f32_e32 v56, v25
	v_fmac_f32_e32 v39, 0x32a5705f, v24
	v_sub_f32_e32 v25, v25, v56
	v_add_f32_e32 v25, v25, v39
	v_exp_f32_e32 v25, v25
	v_cvt_i32_f32_e32 v39, v56
	v_cmp_ngt_f32_e32 vcc, s5, v24
	v_ldexp_f32 v25, v25, v39
	s_nop 0
	v_cndmask_b32_e32 v25, 0, v25, vcc
	v_cmp_nlt_f32_e32 vcc, s6, v24
	s_nop 1
	v_cndmask_b32_e32 v24, v219, v25, vcc
	v_mul_f32_e32 v145, v24, v145
	global_store_dword v[176:177], v145, off
	v_add_u32_e32 v174, 1, v174
	v_lshl_add_u64 v[176:177], v[176:177], 0, s[14:15]
	v_and_b32_e32 v24, 0x1ff, v174
	v_cvt_f32_u32_e32 v24, v24
	v_fmamk_f32 v55, v24, 0xbcc4df2d, v60
	v_mul_f32_e64 v24, |v55|, v173
	v_mul_f32_e32 v25, 0x3fb8aa3b, v24
	v_fma_f32 v39, v24, s4, -v25
	v_rndne_f32_e32 v56, v25
	v_fmac_f32_e32 v39, 0x32a5705f, v24
	v_sub_f32_e32 v25, v25, v56
	v_add_f32_e32 v25, v25, v39
	v_exp_f32_e32 v25, v25
	v_cvt_i32_f32_e32 v39, v56
	v_cmp_ngt_f32_e32 vcc, s5, v24
	v_ldexp_f32 v25, v25, v39
	s_nop 0
	v_cndmask_b32_e32 v25, 0, v25, vcc
	v_cmp_nlt_f32_e32 vcc, s6, v24
	s_nop 1
	v_cndmask_b32_e32 v24, v219, v25, vcc
	v_mul_f32_e32 v146, v24, v146
	global_store_dword v[176:177], v146, off
	v_add_u32_e32 v174, 1, v174
	v_lshl_add_u64 v[176:177], v[176:177], 0, s[14:15]
	v_and_b32_e32 v24, 0x1ff, v174
	v_cvt_f32_u32_e32 v24, v24
	v_fmamk_f32 v55, v24, 0xbcc4df2d, v60
	v_mul_f32_e64 v24, |v55|, v173
	v_mul_f32_e32 v25, 0x3fb8aa3b, v24
	v_fma_f32 v39, v24, s4, -v25
	v_rndne_f32_e32 v56, v25
	v_fmac_f32_e32 v39, 0x32a5705f, v24
	v_sub_f32_e32 v25, v25, v56
	v_add_f32_e32 v25, v25, v39
	v_exp_f32_e32 v25, v25
	v_cvt_i32_f32_e32 v39, v56
	v_cmp_ngt_f32_e32 vcc, s5, v24
	v_ldexp_f32 v25, v25, v39
	s_nop 0
	v_cndmask_b32_e32 v25, 0, v25, vcc
	v_cmp_nlt_f32_e32 vcc, s6, v24
	s_nop 1
	v_cndmask_b32_e32 v24, v219, v25, vcc
	v_mul_f32_e32 v147, v24, v147
	global_store_dword v[176:177], v147, off
	v_add_u32_e32 v174, 5, v174
	v_lshl_add_u64 v[176:177], v[176:177], 0, s[16:17]
	v_and_b32_e32 v24, 0x1ff, v174
	v_cvt_f32_u32_e32 v24, v24
	v_fmamk_f32 v55, v24, 0xbcc4df2d, v60
	v_mul_f32_e64 v24, |v55|, v173
	v_mul_f32_e32 v25, 0x3fb8aa3b, v24
	v_fma_f32 v39, v24, s4, -v25
	v_rndne_f32_e32 v56, v25
	v_fmac_f32_e32 v39, 0x32a5705f, v24
	v_sub_f32_e32 v25, v25, v56
	v_add_f32_e32 v25, v25, v39
	v_exp_f32_e32 v25, v25
	v_cvt_i32_f32_e32 v39, v56
	v_cmp_ngt_f32_e32 vcc, s5, v24
	v_ldexp_f32 v25, v25, v39
	s_nop 0
	v_cndmask_b32_e32 v25, 0, v25, vcc
	v_cmp_nlt_f32_e32 vcc, s6, v24
	s_nop 1
	v_cndmask_b32_e32 v24, v219, v25, vcc
	v_mul_f32_e32 v148, v24, v148
	global_store_dword v[176:177], v148, off
	v_add_u32_e32 v174, 1, v174
	v_lshl_add_u64 v[176:177], v[176:177], 0, s[14:15]
	v_and_b32_e32 v24, 0x1ff, v174
	v_cvt_f32_u32_e32 v24, v24
	v_fmamk_f32 v55, v24, 0xbcc4df2d, v60
	v_mul_f32_e64 v24, |v55|, v173
	v_mul_f32_e32 v25, 0x3fb8aa3b, v24
	v_fma_f32 v39, v24, s4, -v25
	v_rndne_f32_e32 v56, v25
	v_fmac_f32_e32 v39, 0x32a5705f, v24
	v_sub_f32_e32 v25, v25, v56
	v_add_f32_e32 v25, v25, v39
	v_exp_f32_e32 v25, v25
	v_cvt_i32_f32_e32 v39, v56
	v_cmp_ngt_f32_e32 vcc, s5, v24
	v_ldexp_f32 v25, v25, v39
	s_nop 0
	v_cndmask_b32_e32 v25, 0, v25, vcc
	v_cmp_nlt_f32_e32 vcc, s6, v24
	s_nop 1
	v_cndmask_b32_e32 v24, v219, v25, vcc
	v_mul_f32_e32 v149, v24, v149
	global_store_dword v[176:177], v149, off
	v_add_u32_e32 v174, 1, v174
	v_lshl_add_u64 v[176:177], v[176:177], 0, s[14:15]
	v_and_b32_e32 v24, 0x1ff, v174
	v_cvt_f32_u32_e32 v24, v24
	v_fmamk_f32 v55, v24, 0xbcc4df2d, v60
	v_mul_f32_e64 v24, |v55|, v173
	v_mul_f32_e32 v25, 0x3fb8aa3b, v24
	v_fma_f32 v39, v24, s4, -v25
	v_rndne_f32_e32 v56, v25
	v_fmac_f32_e32 v39, 0x32a5705f, v24
	v_sub_f32_e32 v25, v25, v56
	v_add_f32_e32 v25, v25, v39
	v_exp_f32_e32 v25, v25
	v_cvt_i32_f32_e32 v39, v56
	v_cmp_ngt_f32_e32 vcc, s5, v24
	v_ldexp_f32 v25, v25, v39
	s_nop 0
	v_cndmask_b32_e32 v25, 0, v25, vcc
	v_cmp_nlt_f32_e32 vcc, s6, v24
	s_nop 1
	v_cndmask_b32_e32 v24, v219, v25, vcc
	v_mul_f32_e32 v150, v24, v150
	global_store_dword v[176:177], v150, off
	v_add_u32_e32 v174, 1, v174
	v_lshl_add_u64 v[176:177], v[176:177], 0, s[14:15]
	v_and_b32_e32 v24, 0x1ff, v174
	v_cvt_f32_u32_e32 v24, v24
	v_fmamk_f32 v55, v24, 0xbcc4df2d, v60
	v_mul_f32_e64 v24, |v55|, v173
	v_mul_f32_e32 v25, 0x3fb8aa3b, v24
	v_fma_f32 v39, v24, s4, -v25
	v_rndne_f32_e32 v56, v25
	v_fmac_f32_e32 v39, 0x32a5705f, v24
	v_sub_f32_e32 v25, v25, v56
	v_add_f32_e32 v25, v25, v39
	v_exp_f32_e32 v25, v25
	v_cvt_i32_f32_e32 v39, v56
	v_cmp_ngt_f32_e32 vcc, s5, v24
	v_ldexp_f32 v25, v25, v39
	s_nop 0
	v_cndmask_b32_e32 v25, 0, v25, vcc
	v_cmp_nlt_f32_e32 vcc, s6, v24
	s_nop 1
	v_cndmask_b32_e32 v24, v219, v25, vcc
	v_mul_f32_e32 v151, v24, v151
	global_store_dword v[176:177], v151, off
	v_add_u32_e32 v174, 5, v174
	v_lshl_add_u64 v[176:177], v[176:177], 0, s[16:17]
	v_and_b32_e32 v24, 0x1ff, v174
	v_cvt_f32_u32_e32 v24, v24
	v_fmamk_f32 v55, v24, 0xbcc4df2d, v60
	v_mul_f32_e64 v24, |v55|, v173
	v_mul_f32_e32 v25, 0x3fb8aa3b, v24
	v_fma_f32 v39, v24, s4, -v25
	v_rndne_f32_e32 v56, v25
	v_fmac_f32_e32 v39, 0x32a5705f, v24
	v_sub_f32_e32 v25, v25, v56
	v_add_f32_e32 v25, v25, v39
	v_exp_f32_e32 v25, v25
	v_cvt_i32_f32_e32 v39, v56
	v_cmp_ngt_f32_e32 vcc, s5, v24
	v_ldexp_f32 v25, v25, v39
	s_nop 0
	v_cndmask_b32_e32 v25, 0, v25, vcc
	v_cmp_nlt_f32_e32 vcc, s6, v24
	s_nop 1
	v_cndmask_b32_e32 v24, v219, v25, vcc
	v_mul_f32_e32 v152, v24, v152
	global_store_dword v[176:177], v152, off
	v_add_u32_e32 v174, 1, v174
	v_lshl_add_u64 v[176:177], v[176:177], 0, s[14:15]
	v_and_b32_e32 v24, 0x1ff, v174
	v_cvt_f32_u32_e32 v24, v24
	v_fmamk_f32 v55, v24, 0xbcc4df2d, v60
	v_mul_f32_e64 v24, |v55|, v173
	v_mul_f32_e32 v25, 0x3fb8aa3b, v24
	v_fma_f32 v39, v24, s4, -v25
	v_rndne_f32_e32 v56, v25
	v_fmac_f32_e32 v39, 0x32a5705f, v24
	v_sub_f32_e32 v25, v25, v56
	v_add_f32_e32 v25, v25, v39
	v_exp_f32_e32 v25, v25
	v_cvt_i32_f32_e32 v39, v56
	v_cmp_ngt_f32_e32 vcc, s5, v24
	v_ldexp_f32 v25, v25, v39
	s_nop 0
	v_cndmask_b32_e32 v25, 0, v25, vcc
	v_cmp_nlt_f32_e32 vcc, s6, v24
	s_nop 1
	v_cndmask_b32_e32 v24, v219, v25, vcc
	v_mul_f32_e32 v153, v24, v153
	global_store_dword v[176:177], v153, off
	v_add_u32_e32 v174, 1, v174
	v_lshl_add_u64 v[176:177], v[176:177], 0, s[14:15]
	v_and_b32_e32 v24, 0x1ff, v174
	v_cvt_f32_u32_e32 v24, v24
	v_fmamk_f32 v55, v24, 0xbcc4df2d, v60
	v_mul_f32_e64 v24, |v55|, v173
	v_mul_f32_e32 v25, 0x3fb8aa3b, v24
	v_fma_f32 v39, v24, s4, -v25
	v_rndne_f32_e32 v56, v25
	v_fmac_f32_e32 v39, 0x32a5705f, v24
	v_sub_f32_e32 v25, v25, v56
	v_add_f32_e32 v25, v25, v39
	v_exp_f32_e32 v25, v25
	v_cvt_i32_f32_e32 v39, v56
	v_cmp_ngt_f32_e32 vcc, s5, v24
	v_ldexp_f32 v25, v25, v39
	s_nop 0
	v_cndmask_b32_e32 v25, 0, v25, vcc
	v_cmp_nlt_f32_e32 vcc, s6, v24
	s_nop 1
	v_cndmask_b32_e32 v24, v219, v25, vcc
	v_mul_f32_e32 v154, v24, v154
	global_store_dword v[176:177], v154, off
	v_add_u32_e32 v174, 1, v174
	v_lshl_add_u64 v[176:177], v[176:177], 0, s[14:15]
	v_and_b32_e32 v24, 0x1ff, v174
	v_cvt_f32_u32_e32 v24, v24
	v_fmamk_f32 v55, v24, 0xbcc4df2d, v60
	v_mul_f32_e64 v24, |v55|, v173
	v_mul_f32_e32 v25, 0x3fb8aa3b, v24
	v_fma_f32 v39, v24, s4, -v25
	v_rndne_f32_e32 v56, v25
	v_fmac_f32_e32 v39, 0x32a5705f, v24
	v_sub_f32_e32 v25, v25, v56
	v_add_f32_e32 v25, v25, v39
	v_exp_f32_e32 v25, v25
	v_cvt_i32_f32_e32 v39, v56
	v_cmp_ngt_f32_e32 vcc, s5, v24
	v_ldexp_f32 v25, v25, v39
	s_nop 0
	v_cndmask_b32_e32 v25, 0, v25, vcc
	v_cmp_nlt_f32_e32 vcc, s6, v24
	s_nop 1
	v_cndmask_b32_e32 v24, v219, v25, vcc
	v_mul_f32_e32 v155, v24, v155
	global_store_dword v[176:177], v155, off
	v_readlane_b32 s12, v254, 39
	v_readlane_b32 s13, v254, 40
	v_readlane_b32 s14, v254, 41
	v_readlane_b32 s15, v254, 42
	v_readlane_b32 s16, v254, 43
	v_readlane_b32 s17, v254, 44
	v_readlane_b32 s18, v254, 45
	v_readlane_b32 s19, v254, 46
	v_readlane_b32 s20, v254, 47
	v_readlane_b32 s21, v254, 48
	v_readlane_b32 s22, v254, 49
	v_readlane_b32 s23, v254, 50
	v_readlane_b32 s24, v254, 51
	v_readlane_b32 s25, v254, 52
	v_readlane_b32 s26, v254, 53
	v_readlane_b32 s27, v254, 54
	v_readlane_b32 s0, v251, 20
	v_readlane_b32 s1, v251, 21
	s_nop 4
	s_load_dword s0, s[0:1], 0x0
	s_waitcnt lgkmcnt(0)
	s_add_i32 s8, s8, s0
	s_cmpk_gt_i32 s8, 0x81f
	s_cbranch_scc0 .LBB0_1321
